# P1 half-unit K-loop as one straight-line loop per wave half: no wave-half branches, LDS-DMA as SGPR base + lane offset, LDS read bases set once, last four K-tiles peeled
# speedup vs baseline: 1.0075x; 1.0027x over previous
.LBB0_104:
	s_ashr_i32 s65, s64, 31
	s_lshl_b64 s[2:3], s[64:65], 19
	s_add_u32 s2, s80, s2
	s_addc_u32 s3, s81, s3
	s_cmp_gt_i32 s42, 0
	s_cselect_b32 s4, 0x40000, 0
	s_add_u32 s68, s2, s4
	s_addc_u32 s69, s3, 0
	s_and_b64 s[2:3], s[66:67], exec
	s_cselect_b32 s4, s69, s77
	s_cselect_b32 s43, s68, s76
	s_ashr_i32 s63, s62, 31
	s_lshl_b64 s[2:3], s[62:63], 19
	s_add_u32 s70, s10, s2
	s_addc_u32 s71, s11, s3
	s_and_b64 s[2:3], s[66:67], exec
	s_cselect_b32 s63, s71, s1
	s_cselect_b32 s65, s70, s0
	s_cmp_lt_i32 s33, 0
	v_mov_b32_e32 v4, v2
	v_mov_b32_e32 v5, v2
	s_cselect_b64 s[86:87], -1, 0
	s_add_u32 s36, s0, 0x100
	v_mov_b32_e32 v3, v2
	v_mov_b64_e32 v[70:71], v[4:5]
	v_mov_b64_e32 v[72:73], v[4:5]
	v_mov_b64_e32 v[74:75], v[4:5]
	v_mov_b64_e32 v[76:77], v[4:5]
	v_mov_b64_e32 v[78:79], v[4:5]
	v_mov_b64_e32 v[80:81], v[4:5]
	v_mov_b64_e32 v[82:83], v[4:5]
	v_mov_b64_e32 v[84:85], v[4:5]
	v_mov_b64_e32 v[86:87], v[4:5]
	v_mov_b64_e32 v[88:89], v[4:5]
	v_mov_b64_e32 v[90:91], v[4:5]
	v_mov_b64_e32 v[92:93], v[4:5]
	v_mov_b64_e32 v[94:95], v[4:5]
	v_mov_b64_e32 v[96:97], v[4:5]
	v_mov_b64_e32 v[98:99], v[4:5]
	v_mov_b64_e32 v[100:101], v[4:5]
	v_mov_b64_e32 v[102:103], v[4:5]
	v_mov_b64_e32 v[104:105], v[4:5]
	v_mov_b64_e32 v[106:107], v[4:5]
	v_mov_b64_e32 v[108:109], v[4:5]
	v_mov_b64_e32 v[110:111], v[4:5]
	v_mov_b64_e32 v[112:113], v[4:5]
	v_mov_b64_e32 v[114:115], v[4:5]
	v_mov_b64_e32 v[116:117], v[4:5]
	v_mov_b64_e32 v[118:119], v[4:5]
	v_mov_b64_e32 v[120:121], v[4:5]
	v_mov_b64_e32 v[122:123], v[4:5]
	v_mov_b64_e32 v[124:125], v[4:5]
	v_mov_b64_e32 v[126:127], v[4:5]
	v_mov_b64_e32 v[128:129], v[4:5]
	v_mov_b64_e32 v[130:131], v[4:5]
	v_mov_b64_e32 v[132:133], v[4:5]
	v_mov_b64_e32 v[24:25], v[4:5]
	v_mov_b64_e32 v[56:57], v[4:5]
	v_mov_b64_e32 v[28:29], v[4:5]
	v_mov_b64_e32 v[60:61], v[4:5]
	v_mov_b64_e32 v[36:37], v[4:5]
	v_mov_b64_e32 v[68:69], v[4:5]
	v_mov_b64_e32 v[32:33], v[4:5]
	v_mov_b64_e32 v[64:65], v[4:5]
	v_mov_b64_e32 v[12:13], v[4:5]
	v_mov_b64_e32 v[44:45], v[4:5]
	v_mov_b64_e32 v[16:17], v[4:5]
	v_mov_b64_e32 v[48:49], v[4:5]
	v_mov_b64_e32 v[20:21], v[4:5]
	v_mov_b64_e32 v[52:53], v[4:5]
	v_mov_b64_e32 v[8:9], v[4:5]
	v_mov_b64_e32 v[40:41], v[4:5]
	s_addc_u32 s44, s1, 0
	s_mov_b32 s45, -2
	v_mov_b64_e32 v[22:23], v[2:3]
	v_mov_b64_e32 v[54:55], v[2:3]
	v_mov_b64_e32 v[26:27], v[2:3]
	v_mov_b64_e32 v[58:59], v[2:3]
	v_mov_b64_e32 v[34:35], v[2:3]
	v_mov_b64_e32 v[66:67], v[2:3]
	v_mov_b64_e32 v[30:31], v[2:3]
	v_mov_b64_e32 v[62:63], v[2:3]
	v_mov_b64_e32 v[10:11], v[2:3]
	v_mov_b64_e32 v[42:43], v[2:3]
	v_mov_b64_e32 v[14:15], v[2:3]
	v_mov_b64_e32 v[46:47], v[2:3]
	v_mov_b64_e32 v[18:19], v[2:3]
	v_mov_b64_e32 v[50:51], v[2:3]
	v_mov_b64_e32 v[6:7], v[2:3]
	v_mov_b64_e32 v[38:39], v[2:3]
	s_and_b64 vcc, exec, s[86:87]
	s_cbranch_vccnz .LBB0_107
	s_add_u32 s2, s0, 0x100
	s_addc_u32 s3, s1, 0
	s_add_u32 s84, s76, 0x100
	s_addc_u32 s85, s77, 0
	v_add_u32_e32 v220, 0x18000, v247
	v_add_u32_e32 v221, 0x1c000, v247
	v_add_u32_e32 v222, 0xc000, v247
	v_add_u32_e32 v223, 0x20000, v247
	s_mov_b32 s45, 0
	s_waitcnt vmcnt(0)
	s_and_b64 vcc, exec, s[14:15]
	s_cbranch_vccz .Lhu_y
.Lhu_x:
	ds_read_b128 v[150:153], v248
	ds_read_b128 v[154:157], v248 offset:1024
	ds_read_b128 v[158:161], v248 offset:2048
	ds_read_b128 v[162:165], v248 offset:3072
	ds_read_b128 v[134:137], v249
	ds_read_b128 v[138:141], v249 offset:1024
	ds_read_b128 v[142:145], v249 offset:2048
	ds_read_b128 v[146:149], v249 offset:3072
	ds_read_b128 v[166:169], v250
	ds_read_b128 v[170:173], v250 offset:1024
	ds_read_b128 v[174:177], v250 offset:2048
	ds_read_b128 v[178:181], v250 offset:3072
	ds_read_b128 v[182:185], v250 offset:4096
	ds_read_b128 v[186:189], v250 offset:5120
	ds_read_b128 v[190:193], v250 offset:6144
	ds_read_b128 v[194:197], v250 offset:7168
	s_add_u32 s88, s2, 0x40000
	s_addc_u32 s89, s3, 0
	s_add_i32 m0, s61, 0xc000
	s_nop 0
	global_load_lds_dwordx4 v208, s[2:3]
	s_add_i32 m0, s61, 0xe000
	s_nop 0
	global_load_lds_dwordx4 v212, s[2:3]
	s_add_i32 m0, s61, 0x20000
	s_nop 0
	global_load_lds_dwordx4 v208, s[88:89]
	s_add_i32 m0, s61, 0x22000
	s_nop 0
	global_load_lds_dwordx4 v212, s[88:89]
	s_mov_b32 m0, s95
	s_nop 0
	global_load_lds_dwordx4 v206, s[84:85]
	s_mov_b32 m0, s96
	s_nop 0
	global_load_lds_dwordx4 v210, s[84:85]
	s_add_u32 s2, s2, 0x80
	s_addc_u32 s3, s3, 0
	s_add_u32 s84, s84, 0x80
	s_addc_u32 s85, s85, 0
	s_setprio 1
	s_waitcnt lgkmcnt(0)
	s_barrier
	v_mfma_f32_16x16x32_bf16 v[102:105], v[150:153], v[166:169], v[102:105]
	v_mfma_f32_16x16x32_bf16 v[70:73], v[158:161], v[166:169], v[70:73]
	v_mfma_f32_16x16x32_bf16 v[114:117], v[150:153], v[174:177], v[114:117]
	v_mfma_f32_16x16x32_bf16 v[82:85], v[158:161], v[174:177], v[82:85]
	v_mfma_f32_16x16x32_bf16 v[110:113], v[150:153], v[182:185], v[110:113]
	v_mfma_f32_16x16x32_bf16 v[78:81], v[158:161], v[182:185], v[78:81]
	v_mfma_f32_16x16x32_bf16 v[106:109], v[150:153], v[190:193], v[106:109]
	v_mfma_f32_16x16x32_bf16 v[74:77], v[158:161], v[190:193], v[74:77]
	v_mfma_f32_16x16x32_bf16 v[102:105], v[154:157], v[170:173], v[102:105]
	v_mfma_f32_16x16x32_bf16 v[70:73], v[162:165], v[170:173], v[70:73]
	v_mfma_f32_16x16x32_bf16 v[114:117], v[154:157], v[178:181], v[114:117]
	v_mfma_f32_16x16x32_bf16 v[82:85], v[162:165], v[178:181], v[82:85]
	v_mfma_f32_16x16x32_bf16 v[110:113], v[154:157], v[186:189], v[110:113]
	v_mfma_f32_16x16x32_bf16 v[78:81], v[162:165], v[186:189], v[78:81]
	v_mfma_f32_16x16x32_bf16 v[106:109], v[154:157], v[194:197], v[106:109]
	v_mfma_f32_16x16x32_bf16 v[74:77], v[162:165], v[194:197], v[74:77]
	v_mfma_f32_16x16x32_bf16 v[130:133], v[134:137], v[166:169], v[130:133]
	v_mfma_f32_16x16x32_bf16 v[98:101], v[142:145], v[166:169], v[98:101]
	v_mfma_f32_16x16x32_bf16 v[126:129], v[134:137], v[174:177], v[126:129]
	v_mfma_f32_16x16x32_bf16 v[94:97], v[142:145], v[174:177], v[94:97]
	v_mfma_f32_16x16x32_bf16 v[122:125], v[134:137], v[182:185], v[122:125]
	v_mfma_f32_16x16x32_bf16 v[90:93], v[142:145], v[182:185], v[90:93]
	v_mfma_f32_16x16x32_bf16 v[118:121], v[134:137], v[190:193], v[118:121]
	v_mfma_f32_16x16x32_bf16 v[86:89], v[142:145], v[190:193], v[86:89]
	v_mfma_f32_16x16x32_bf16 v[130:133], v[138:141], v[170:173], v[130:133]
	v_mfma_f32_16x16x32_bf16 v[98:101], v[146:149], v[170:173], v[98:101]
	v_mfma_f32_16x16x32_bf16 v[126:129], v[138:141], v[178:181], v[126:129]
	v_mfma_f32_16x16x32_bf16 v[94:97], v[146:149], v[178:181], v[94:97]
	v_mfma_f32_16x16x32_bf16 v[122:125], v[138:141], v[186:189], v[122:125]
	v_mfma_f32_16x16x32_bf16 v[90:93], v[146:149], v[186:189], v[90:93]
	v_mfma_f32_16x16x32_bf16 v[118:121], v[138:141], v[194:197], v[118:121]
	v_mfma_f32_16x16x32_bf16 v[86:89], v[146:149], v[194:197], v[86:89]
	s_waitcnt vmcnt(6)
	s_barrier
	s_setprio 0
	ds_read_b128 v[150:153], v220
	ds_read_b128 v[154:157], v220 offset:1024
	ds_read_b128 v[158:161], v220 offset:2048
	ds_read_b128 v[162:165], v220 offset:3072
	ds_read_b128 v[134:137], v221
	ds_read_b128 v[138:141], v221 offset:1024
	ds_read_b128 v[142:145], v221 offset:2048
	ds_read_b128 v[146:149], v221 offset:3072
	ds_read_b128 v[166:169], v250 offset:32768
	ds_read_b128 v[170:173], v250 offset:33792
	ds_read_b128 v[174:177], v250 offset:34816
	ds_read_b128 v[178:181], v250 offset:35840
	ds_read_b128 v[182:185], v250 offset:36864
	ds_read_b128 v[186:189], v250 offset:37888
	ds_read_b128 v[190:193], v250 offset:38912
	ds_read_b128 v[194:197], v250 offset:39936
	s_add_u32 s88, s2, 0x40000
	s_addc_u32 s89, s3, 0
	s_mov_b32 m0, s73
	s_nop 0
	global_load_lds_dwordx4 v208, s[2:3]
	s_mov_b32 m0, s75
	s_nop 0
	global_load_lds_dwordx4 v212, s[2:3]
	s_mov_b32 m0, s92
	s_nop 0
	global_load_lds_dwordx4 v208, s[88:89]
	s_mov_b32 m0, s93
	s_nop 0
	global_load_lds_dwordx4 v212, s[88:89]
	s_mov_b32 m0, s61
	s_nop 0
	global_load_lds_dwordx4 v206, s[84:85]
	s_mov_b32 m0, s94
	s_nop 0
	global_load_lds_dwordx4 v210, s[84:85]
	s_add_u32 s2, s2, 0x80
	s_addc_u32 s3, s3, 0
	s_add_u32 s84, s84, 0x80
	s_addc_u32 s85, s85, 0
	s_setprio 1
	s_waitcnt lgkmcnt(0)
	s_barrier
	v_mfma_f32_16x16x32_bf16 v[102:105], v[150:153], v[166:169], v[102:105]
	v_mfma_f32_16x16x32_bf16 v[70:73], v[158:161], v[166:169], v[70:73]
	v_mfma_f32_16x16x32_bf16 v[114:117], v[150:153], v[174:177], v[114:117]
	v_mfma_f32_16x16x32_bf16 v[82:85], v[158:161], v[174:177], v[82:85]
	v_mfma_f32_16x16x32_bf16 v[110:113], v[150:153], v[182:185], v[110:113]
	v_mfma_f32_16x16x32_bf16 v[78:81], v[158:161], v[182:185], v[78:81]
	v_mfma_f32_16x16x32_bf16 v[106:109], v[150:153], v[190:193], v[106:109]
	v_mfma_f32_16x16x32_bf16 v[74:77], v[158:161], v[190:193], v[74:77]
	v_mfma_f32_16x16x32_bf16 v[102:105], v[154:157], v[170:173], v[102:105]
	v_mfma_f32_16x16x32_bf16 v[70:73], v[162:165], v[170:173], v[70:73]
	v_mfma_f32_16x16x32_bf16 v[114:117], v[154:157], v[178:181], v[114:117]
	v_mfma_f32_16x16x32_bf16 v[82:85], v[162:165], v[178:181], v[82:85]
	v_mfma_f32_16x16x32_bf16 v[110:113], v[154:157], v[186:189], v[110:113]
	v_mfma_f32_16x16x32_bf16 v[78:81], v[162:165], v[186:189], v[78:81]
	v_mfma_f32_16x16x32_bf16 v[106:109], v[154:157], v[194:197], v[106:109]
	v_mfma_f32_16x16x32_bf16 v[74:77], v[162:165], v[194:197], v[74:77]
	v_mfma_f32_16x16x32_bf16 v[130:133], v[134:137], v[166:169], v[130:133]
	v_mfma_f32_16x16x32_bf16 v[98:101], v[142:145], v[166:169], v[98:101]
	v_mfma_f32_16x16x32_bf16 v[126:129], v[134:137], v[174:177], v[126:129]
	v_mfma_f32_16x16x32_bf16 v[94:97], v[142:145], v[174:177], v[94:97]
	v_mfma_f32_16x16x32_bf16 v[122:125], v[134:137], v[182:185], v[122:125]
	v_mfma_f32_16x16x32_bf16 v[90:93], v[142:145], v[182:185], v[90:93]
	v_mfma_f32_16x16x32_bf16 v[118:121], v[134:137], v[190:193], v[118:121]
	v_mfma_f32_16x16x32_bf16 v[86:89], v[142:145], v[190:193], v[86:89]
	v_mfma_f32_16x16x32_bf16 v[130:133], v[138:141], v[170:173], v[130:133]
	v_mfma_f32_16x16x32_bf16 v[98:101], v[146:149], v[170:173], v[98:101]
	v_mfma_f32_16x16x32_bf16 v[126:129], v[138:141], v[178:181], v[126:129]
	v_mfma_f32_16x16x32_bf16 v[94:97], v[146:149], v[178:181], v[94:97]
	v_mfma_f32_16x16x32_bf16 v[122:125], v[138:141], v[186:189], v[122:125]
	v_mfma_f32_16x16x32_bf16 v[90:93], v[146:149], v[186:189], v[90:93]
	v_mfma_f32_16x16x32_bf16 v[118:121], v[138:141], v[194:197], v[118:121]
	v_mfma_f32_16x16x32_bf16 v[86:89], v[146:149], v[194:197], v[86:89]
	s_waitcnt vmcnt(6)
	s_barrier
	s_setprio 0
	ds_read_b128 v[150:153], v222
	ds_read_b128 v[154:157], v222 offset:1024
	ds_read_b128 v[158:161], v222 offset:2048
	ds_read_b128 v[162:165], v222 offset:3072
	ds_read_b128 v[134:137], v223
	ds_read_b128 v[138:141], v223 offset:1024
	ds_read_b128 v[142:145], v223 offset:2048
	ds_read_b128 v[146:149], v223 offset:3072
	ds_read_b128 v[166:169], v250 offset:16384
	ds_read_b128 v[170:173], v250 offset:17408
	ds_read_b128 v[174:177], v250 offset:18432
	ds_read_b128 v[178:181], v250 offset:19456
	ds_read_b128 v[182:185], v250 offset:20480
	ds_read_b128 v[186:189], v250 offset:21504
	ds_read_b128 v[190:193], v250 offset:22528
	ds_read_b128 v[194:197], v250 offset:23552
	s_add_u32 s88, s2, 0x40000
	s_addc_u32 s89, s3, 0
	s_mov_b32 m0, s54
	s_nop 0
	global_load_lds_dwordx4 v208, s[2:3]
	s_mov_b32 m0, s55
	s_nop 0
	global_load_lds_dwordx4 v212, s[2:3]
	s_mov_b32 m0, s59
	s_nop 0
	global_load_lds_dwordx4 v208, s[88:89]
	s_mov_b32 m0, s24
	s_nop 0
	global_load_lds_dwordx4 v212, s[88:89]
	s_mov_b32 m0, s57
	s_nop 0
	global_load_lds_dwordx4 v206, s[84:85]
	s_mov_b32 m0, s58
	s_nop 0
	global_load_lds_dwordx4 v210, s[84:85]
	s_add_u32 s2, s2, 0x80
	s_addc_u32 s3, s3, 0
	s_add_u32 s84, s84, 0x80
	s_addc_u32 s85, s85, 0
	s_setprio 1
	s_waitcnt lgkmcnt(0)
	s_barrier
	v_mfma_f32_16x16x32_bf16 v[102:105], v[150:153], v[166:169], v[102:105]
	v_mfma_f32_16x16x32_bf16 v[70:73], v[158:161], v[166:169], v[70:73]
	v_mfma_f32_16x16x32_bf16 v[114:117], v[150:153], v[174:177], v[114:117]
	v_mfma_f32_16x16x32_bf16 v[82:85], v[158:161], v[174:177], v[82:85]
	v_mfma_f32_16x16x32_bf16 v[110:113], v[150:153], v[182:185], v[110:113]
	v_mfma_f32_16x16x32_bf16 v[78:81], v[158:161], v[182:185], v[78:81]
	v_mfma_f32_16x16x32_bf16 v[106:109], v[150:153], v[190:193], v[106:109]
	v_mfma_f32_16x16x32_bf16 v[74:77], v[158:161], v[190:193], v[74:77]
	v_mfma_f32_16x16x32_bf16 v[102:105], v[154:157], v[170:173], v[102:105]
	v_mfma_f32_16x16x32_bf16 v[70:73], v[162:165], v[170:173], v[70:73]
	v_mfma_f32_16x16x32_bf16 v[114:117], v[154:157], v[178:181], v[114:117]
	v_mfma_f32_16x16x32_bf16 v[82:85], v[162:165], v[178:181], v[82:85]
	v_mfma_f32_16x16x32_bf16 v[110:113], v[154:157], v[186:189], v[110:113]
	v_mfma_f32_16x16x32_bf16 v[78:81], v[162:165], v[186:189], v[78:81]
	v_mfma_f32_16x16x32_bf16 v[106:109], v[154:157], v[194:197], v[106:109]
	v_mfma_f32_16x16x32_bf16 v[74:77], v[162:165], v[194:197], v[74:77]
	v_mfma_f32_16x16x32_bf16 v[130:133], v[134:137], v[166:169], v[130:133]
	v_mfma_f32_16x16x32_bf16 v[98:101], v[142:145], v[166:169], v[98:101]
	v_mfma_f32_16x16x32_bf16 v[126:129], v[134:137], v[174:177], v[126:129]
	v_mfma_f32_16x16x32_bf16 v[94:97], v[142:145], v[174:177], v[94:97]
	v_mfma_f32_16x16x32_bf16 v[122:125], v[134:137], v[182:185], v[122:125]
	v_mfma_f32_16x16x32_bf16 v[90:93], v[142:145], v[182:185], v[90:93]
	v_mfma_f32_16x16x32_bf16 v[118:121], v[134:137], v[190:193], v[118:121]
	v_mfma_f32_16x16x32_bf16 v[86:89], v[142:145], v[190:193], v[86:89]
	v_mfma_f32_16x16x32_bf16 v[130:133], v[138:141], v[170:173], v[130:133]
	v_mfma_f32_16x16x32_bf16 v[98:101], v[146:149], v[170:173], v[98:101]
	v_mfma_f32_16x16x32_bf16 v[126:129], v[138:141], v[178:181], v[126:129]
	v_mfma_f32_16x16x32_bf16 v[94:97], v[146:149], v[178:181], v[94:97]
	v_mfma_f32_16x16x32_bf16 v[122:125], v[138:141], v[186:189], v[122:125]
	v_mfma_f32_16x16x32_bf16 v[90:93], v[146:149], v[186:189], v[90:93]
	v_mfma_f32_16x16x32_bf16 v[118:121], v[138:141], v[194:197], v[118:121]
	v_mfma_f32_16x16x32_bf16 v[86:89], v[146:149], v[194:197], v[86:89]
	s_waitcnt vmcnt(6)
	s_barrier
	s_setprio 0
	s_add_i32 s45, s45, 1
	s_cmp_lt_u32 s45, 4
	s_cbranch_scc1 .Lhu_x
	ds_read_b128 v[150:153], v248
	ds_read_b128 v[154:157], v248 offset:1024
	ds_read_b128 v[158:161], v248 offset:2048
	ds_read_b128 v[162:165], v248 offset:3072
	ds_read_b128 v[134:137], v249
	ds_read_b128 v[138:141], v249 offset:1024
	ds_read_b128 v[142:145], v249 offset:2048
	ds_read_b128 v[146:149], v249 offset:3072
	ds_read_b128 v[166:169], v250
	ds_read_b128 v[170:173], v250 offset:1024
	ds_read_b128 v[174:177], v250 offset:2048
	ds_read_b128 v[178:181], v250 offset:3072
	ds_read_b128 v[182:185], v250 offset:4096
	ds_read_b128 v[186:189], v250 offset:5120
	ds_read_b128 v[190:193], v250 offset:6144
	ds_read_b128 v[194:197], v250 offset:7168
	s_add_u32 s88, s2, 0x40000
	s_addc_u32 s89, s3, 0
	s_add_i32 m0, s61, 0xc000
	s_nop 0
	global_load_lds_dwordx4 v208, s[2:3]
	s_add_i32 m0, s61, 0xe000
	s_nop 0
	global_load_lds_dwordx4 v212, s[2:3]
	s_add_i32 m0, s61, 0x20000
	s_nop 0
	global_load_lds_dwordx4 v208, s[88:89]
	s_add_i32 m0, s61, 0x22000
	s_nop 0
	global_load_lds_dwordx4 v212, s[88:89]
	s_mov_b32 m0, s95
	s_nop 0
	global_load_lds_dwordx4 v206, s[84:85]
	s_mov_b32 m0, s96
	s_nop 0
	global_load_lds_dwordx4 v210, s[84:85]
	s_add_u32 s2, s2, 0x80
	s_addc_u32 s3, s3, 0
	s_add_u32 s84, s84, 0x80
	s_addc_u32 s85, s85, 0
	s_setprio 1
	s_waitcnt lgkmcnt(0)
	s_barrier
	v_mfma_f32_16x16x32_bf16 v[102:105], v[150:153], v[166:169], v[102:105]
	v_mfma_f32_16x16x32_bf16 v[70:73], v[158:161], v[166:169], v[70:73]
	v_mfma_f32_16x16x32_bf16 v[114:117], v[150:153], v[174:177], v[114:117]
	v_mfma_f32_16x16x32_bf16 v[82:85], v[158:161], v[174:177], v[82:85]
	v_mfma_f32_16x16x32_bf16 v[110:113], v[150:153], v[182:185], v[110:113]
	v_mfma_f32_16x16x32_bf16 v[78:81], v[158:161], v[182:185], v[78:81]
	v_mfma_f32_16x16x32_bf16 v[106:109], v[150:153], v[190:193], v[106:109]
	v_mfma_f32_16x16x32_bf16 v[74:77], v[158:161], v[190:193], v[74:77]
	v_mfma_f32_16x16x32_bf16 v[102:105], v[154:157], v[170:173], v[102:105]
	v_mfma_f32_16x16x32_bf16 v[70:73], v[162:165], v[170:173], v[70:73]
	v_mfma_f32_16x16x32_bf16 v[114:117], v[154:157], v[178:181], v[114:117]
	v_mfma_f32_16x16x32_bf16 v[82:85], v[162:165], v[178:181], v[82:85]
	v_mfma_f32_16x16x32_bf16 v[110:113], v[154:157], v[186:189], v[110:113]
	v_mfma_f32_16x16x32_bf16 v[78:81], v[162:165], v[186:189], v[78:81]
	v_mfma_f32_16x16x32_bf16 v[106:109], v[154:157], v[194:197], v[106:109]
	v_mfma_f32_16x16x32_bf16 v[74:77], v[162:165], v[194:197], v[74:77]
	v_mfma_f32_16x16x32_bf16 v[130:133], v[134:137], v[166:169], v[130:133]
	v_mfma_f32_16x16x32_bf16 v[98:101], v[142:145], v[166:169], v[98:101]
	v_mfma_f32_16x16x32_bf16 v[126:129], v[134:137], v[174:177], v[126:129]
	v_mfma_f32_16x16x32_bf16 v[94:97], v[142:145], v[174:177], v[94:97]
	v_mfma_f32_16x16x32_bf16 v[122:125], v[134:137], v[182:185], v[122:125]
	v_mfma_f32_16x16x32_bf16 v[90:93], v[142:145], v[182:185], v[90:93]
	v_mfma_f32_16x16x32_bf16 v[118:121], v[134:137], v[190:193], v[118:121]
	v_mfma_f32_16x16x32_bf16 v[86:89], v[142:145], v[190:193], v[86:89]
	v_mfma_f32_16x16x32_bf16 v[130:133], v[138:141], v[170:173], v[130:133]
	v_mfma_f32_16x16x32_bf16 v[98:101], v[146:149], v[170:173], v[98:101]
	v_mfma_f32_16x16x32_bf16 v[126:129], v[138:141], v[178:181], v[126:129]
	v_mfma_f32_16x16x32_bf16 v[94:97], v[146:149], v[178:181], v[94:97]
	v_mfma_f32_16x16x32_bf16 v[122:125], v[138:141], v[186:189], v[122:125]
	v_mfma_f32_16x16x32_bf16 v[90:93], v[146:149], v[186:189], v[90:93]
	v_mfma_f32_16x16x32_bf16 v[118:121], v[138:141], v[194:197], v[118:121]
	v_mfma_f32_16x16x32_bf16 v[86:89], v[146:149], v[194:197], v[86:89]
	s_waitcnt vmcnt(6)
	s_barrier
	s_setprio 0
	ds_read_b128 v[150:153], v220
	ds_read_b128 v[154:157], v220 offset:1024
	ds_read_b128 v[158:161], v220 offset:2048
	ds_read_b128 v[162:165], v220 offset:3072
	ds_read_b128 v[134:137], v221
	ds_read_b128 v[138:141], v221 offset:1024
	ds_read_b128 v[142:145], v221 offset:2048
	ds_read_b128 v[146:149], v221 offset:3072
	ds_read_b128 v[166:169], v250 offset:32768
	ds_read_b128 v[170:173], v250 offset:33792
	ds_read_b128 v[174:177], v250 offset:34816
	ds_read_b128 v[178:181], v250 offset:35840
	ds_read_b128 v[182:185], v250 offset:36864
	ds_read_b128 v[186:189], v250 offset:37888
	ds_read_b128 v[190:193], v250 offset:38912
	ds_read_b128 v[194:197], v250 offset:39936
	s_add_u32 s88, s2, 0x40000
	s_addc_u32 s89, s3, 0
	s_mov_b32 m0, s73
	s_nop 0
	global_load_lds_dwordx4 v208, s[2:3]
	s_mov_b32 m0, s75
	s_nop 0
	global_load_lds_dwordx4 v212, s[2:3]
	s_mov_b32 m0, s92
	s_nop 0
	global_load_lds_dwordx4 v208, s[88:89]
	s_mov_b32 m0, s93
	s_nop 0
	global_load_lds_dwordx4 v212, s[88:89]
	s_mov_b32 m0, s61
	s_nop 0
	global_load_lds_dwordx4 v206, s[84:85]
	s_mov_b32 m0, s94
	s_nop 0
	global_load_lds_dwordx4 v210, s[84:85]
	s_add_u32 s2, s2, 0x80
	s_addc_u32 s3, s3, 0
	s_add_u32 s84, s84, 0x80
	s_addc_u32 s85, s85, 0
	s_setprio 1
	s_waitcnt lgkmcnt(0)
	s_barrier
	v_mfma_f32_16x16x32_bf16 v[102:105], v[150:153], v[166:169], v[102:105]
	v_mfma_f32_16x16x32_bf16 v[70:73], v[158:161], v[166:169], v[70:73]
	v_mfma_f32_16x16x32_bf16 v[114:117], v[150:153], v[174:177], v[114:117]
	v_mfma_f32_16x16x32_bf16 v[82:85], v[158:161], v[174:177], v[82:85]
	v_mfma_f32_16x16x32_bf16 v[110:113], v[150:153], v[182:185], v[110:113]
	v_mfma_f32_16x16x32_bf16 v[78:81], v[158:161], v[182:185], v[78:81]
	v_mfma_f32_16x16x32_bf16 v[106:109], v[150:153], v[190:193], v[106:109]
	v_mfma_f32_16x16x32_bf16 v[74:77], v[158:161], v[190:193], v[74:77]
	v_mfma_f32_16x16x32_bf16 v[102:105], v[154:157], v[170:173], v[102:105]
	v_mfma_f32_16x16x32_bf16 v[70:73], v[162:165], v[170:173], v[70:73]
	v_mfma_f32_16x16x32_bf16 v[114:117], v[154:157], v[178:181], v[114:117]
	v_mfma_f32_16x16x32_bf16 v[82:85], v[162:165], v[178:181], v[82:85]
	v_mfma_f32_16x16x32_bf16 v[110:113], v[154:157], v[186:189], v[110:113]
	v_mfma_f32_16x16x32_bf16 v[78:81], v[162:165], v[186:189], v[78:81]
	v_mfma_f32_16x16x32_bf16 v[106:109], v[154:157], v[194:197], v[106:109]
	v_mfma_f32_16x16x32_bf16 v[74:77], v[162:165], v[194:197], v[74:77]
	v_mfma_f32_16x16x32_bf16 v[130:133], v[134:137], v[166:169], v[130:133]
	v_mfma_f32_16x16x32_bf16 v[98:101], v[142:145], v[166:169], v[98:101]
	v_mfma_f32_16x16x32_bf16 v[126:129], v[134:137], v[174:177], v[126:129]
	v_mfma_f32_16x16x32_bf16 v[94:97], v[142:145], v[174:177], v[94:97]
	v_mfma_f32_16x16x32_bf16 v[122:125], v[134:137], v[182:185], v[122:125]
	v_mfma_f32_16x16x32_bf16 v[90:93], v[142:145], v[182:185], v[90:93]
	v_mfma_f32_16x16x32_bf16 v[118:121], v[134:137], v[190:193], v[118:121]
	v_mfma_f32_16x16x32_bf16 v[86:89], v[142:145], v[190:193], v[86:89]
	v_mfma_f32_16x16x32_bf16 v[130:133], v[138:141], v[170:173], v[130:133]
	v_mfma_f32_16x16x32_bf16 v[98:101], v[146:149], v[170:173], v[98:101]
	v_mfma_f32_16x16x32_bf16 v[126:129], v[138:141], v[178:181], v[126:129]
	v_mfma_f32_16x16x32_bf16 v[94:97], v[146:149], v[178:181], v[94:97]
	v_mfma_f32_16x16x32_bf16 v[122:125], v[138:141], v[186:189], v[122:125]
	v_mfma_f32_16x16x32_bf16 v[90:93], v[146:149], v[186:189], v[90:93]
	v_mfma_f32_16x16x32_bf16 v[118:121], v[138:141], v[194:197], v[118:121]
	v_mfma_f32_16x16x32_bf16 v[86:89], v[146:149], v[194:197], v[86:89]
	s_waitcnt vmcnt(6)
	s_barrier
	s_setprio 0
	ds_read_b128 v[150:153], v222
	ds_read_b128 v[154:157], v222 offset:1024
	ds_read_b128 v[158:161], v222 offset:2048
	ds_read_b128 v[162:165], v222 offset:3072
	ds_read_b128 v[134:137], v223
	ds_read_b128 v[138:141], v223 offset:1024
	ds_read_b128 v[142:145], v223 offset:2048
	ds_read_b128 v[146:149], v223 offset:3072
	ds_read_b128 v[166:169], v250 offset:16384
	ds_read_b128 v[170:173], v250 offset:17408
	ds_read_b128 v[174:177], v250 offset:18432
	ds_read_b128 v[178:181], v250 offset:19456
	ds_read_b128 v[182:185], v250 offset:20480
	ds_read_b128 v[186:189], v250 offset:21504
	ds_read_b128 v[190:193], v250 offset:22528
	ds_read_b128 v[194:197], v250 offset:23552
	s_setprio 1
	s_waitcnt lgkmcnt(0)
	s_barrier
	v_mfma_f32_16x16x32_bf16 v[102:105], v[150:153], v[166:169], v[102:105]
	v_mfma_f32_16x16x32_bf16 v[70:73], v[158:161], v[166:169], v[70:73]
	v_mfma_f32_16x16x32_bf16 v[114:117], v[150:153], v[174:177], v[114:117]
	v_mfma_f32_16x16x32_bf16 v[82:85], v[158:161], v[174:177], v[82:85]
	v_mfma_f32_16x16x32_bf16 v[110:113], v[150:153], v[182:185], v[110:113]
	v_mfma_f32_16x16x32_bf16 v[78:81], v[158:161], v[182:185], v[78:81]
	v_mfma_f32_16x16x32_bf16 v[106:109], v[150:153], v[190:193], v[106:109]
	v_mfma_f32_16x16x32_bf16 v[74:77], v[158:161], v[190:193], v[74:77]
	v_mfma_f32_16x16x32_bf16 v[102:105], v[154:157], v[170:173], v[102:105]
	v_mfma_f32_16x16x32_bf16 v[70:73], v[162:165], v[170:173], v[70:73]
	v_mfma_f32_16x16x32_bf16 v[114:117], v[154:157], v[178:181], v[114:117]
	v_mfma_f32_16x16x32_bf16 v[82:85], v[162:165], v[178:181], v[82:85]
	v_mfma_f32_16x16x32_bf16 v[110:113], v[154:157], v[186:189], v[110:113]
	v_mfma_f32_16x16x32_bf16 v[78:81], v[162:165], v[186:189], v[78:81]
	v_mfma_f32_16x16x32_bf16 v[106:109], v[154:157], v[194:197], v[106:109]
	v_mfma_f32_16x16x32_bf16 v[74:77], v[162:165], v[194:197], v[74:77]
	v_mfma_f32_16x16x32_bf16 v[130:133], v[134:137], v[166:169], v[130:133]
	v_mfma_f32_16x16x32_bf16 v[98:101], v[142:145], v[166:169], v[98:101]
	v_mfma_f32_16x16x32_bf16 v[126:129], v[134:137], v[174:177], v[126:129]
	v_mfma_f32_16x16x32_bf16 v[94:97], v[142:145], v[174:177], v[94:97]
	v_mfma_f32_16x16x32_bf16 v[122:125], v[134:137], v[182:185], v[122:125]
	v_mfma_f32_16x16x32_bf16 v[90:93], v[142:145], v[182:185], v[90:93]
	v_mfma_f32_16x16x32_bf16 v[118:121], v[134:137], v[190:193], v[118:121]
	v_mfma_f32_16x16x32_bf16 v[86:89], v[142:145], v[190:193], v[86:89]
	v_mfma_f32_16x16x32_bf16 v[130:133], v[138:141], v[170:173], v[130:133]
	v_mfma_f32_16x16x32_bf16 v[98:101], v[146:149], v[170:173], v[98:101]
	v_mfma_f32_16x16x32_bf16 v[126:129], v[138:141], v[178:181], v[126:129]
	v_mfma_f32_16x16x32_bf16 v[94:97], v[146:149], v[178:181], v[94:97]
	v_mfma_f32_16x16x32_bf16 v[122:125], v[138:141], v[186:189], v[122:125]
	v_mfma_f32_16x16x32_bf16 v[90:93], v[146:149], v[186:189], v[90:93]
	v_mfma_f32_16x16x32_bf16 v[118:121], v[138:141], v[194:197], v[118:121]
	v_mfma_f32_16x16x32_bf16 v[86:89], v[146:149], v[194:197], v[86:89]
	s_waitcnt vmcnt(0)
	s_barrier
	s_setprio 0
	ds_read_b128 v[150:153], v248
	ds_read_b128 v[154:157], v248 offset:1024
	ds_read_b128 v[158:161], v248 offset:2048
	ds_read_b128 v[162:165], v248 offset:3072
	ds_read_b128 v[134:137], v249
	ds_read_b128 v[138:141], v249 offset:1024
	ds_read_b128 v[142:145], v249 offset:2048
	ds_read_b128 v[146:149], v249 offset:3072
	ds_read_b128 v[166:169], v250
	ds_read_b128 v[170:173], v250 offset:1024
	ds_read_b128 v[174:177], v250 offset:2048
	ds_read_b128 v[178:181], v250 offset:3072
	ds_read_b128 v[182:185], v250 offset:4096
	ds_read_b128 v[186:189], v250 offset:5120
	ds_read_b128 v[190:193], v250 offset:6144
	ds_read_b128 v[194:197], v250 offset:7168
	s_setprio 1
	s_waitcnt lgkmcnt(0)
	s_barrier
	v_mfma_f32_16x16x32_bf16 v[102:105], v[150:153], v[166:169], v[102:105]
	v_mfma_f32_16x16x32_bf16 v[70:73], v[158:161], v[166:169], v[70:73]
	v_mfma_f32_16x16x32_bf16 v[114:117], v[150:153], v[174:177], v[114:117]
	v_mfma_f32_16x16x32_bf16 v[82:85], v[158:161], v[174:177], v[82:85]
	v_mfma_f32_16x16x32_bf16 v[110:113], v[150:153], v[182:185], v[110:113]
	v_mfma_f32_16x16x32_bf16 v[78:81], v[158:161], v[182:185], v[78:81]
	v_mfma_f32_16x16x32_bf16 v[106:109], v[150:153], v[190:193], v[106:109]
	v_mfma_f32_16x16x32_bf16 v[74:77], v[158:161], v[190:193], v[74:77]
	v_mfma_f32_16x16x32_bf16 v[102:105], v[154:157], v[170:173], v[102:105]
	v_mfma_f32_16x16x32_bf16 v[70:73], v[162:165], v[170:173], v[70:73]
	v_mfma_f32_16x16x32_bf16 v[114:117], v[154:157], v[178:181], v[114:117]
	v_mfma_f32_16x16x32_bf16 v[82:85], v[162:165], v[178:181], v[82:85]
	v_mfma_f32_16x16x32_bf16 v[110:113], v[154:157], v[186:189], v[110:113]
	v_mfma_f32_16x16x32_bf16 v[78:81], v[162:165], v[186:189], v[78:81]
	v_mfma_f32_16x16x32_bf16 v[106:109], v[154:157], v[194:197], v[106:109]
	v_mfma_f32_16x16x32_bf16 v[74:77], v[162:165], v[194:197], v[74:77]
	v_mfma_f32_16x16x32_bf16 v[130:133], v[134:137], v[166:169], v[130:133]
	v_mfma_f32_16x16x32_bf16 v[98:101], v[142:145], v[166:169], v[98:101]
	v_mfma_f32_16x16x32_bf16 v[126:129], v[134:137], v[174:177], v[126:129]
	v_mfma_f32_16x16x32_bf16 v[94:97], v[142:145], v[174:177], v[94:97]
	v_mfma_f32_16x16x32_bf16 v[122:125], v[134:137], v[182:185], v[122:125]
	v_mfma_f32_16x16x32_bf16 v[90:93], v[142:145], v[182:185], v[90:93]
	v_mfma_f32_16x16x32_bf16 v[118:121], v[134:137], v[190:193], v[118:121]
	v_mfma_f32_16x16x32_bf16 v[86:89], v[142:145], v[190:193], v[86:89]
	v_mfma_f32_16x16x32_bf16 v[130:133], v[138:141], v[170:173], v[130:133]
	v_mfma_f32_16x16x32_bf16 v[98:101], v[146:149], v[170:173], v[98:101]
	v_mfma_f32_16x16x32_bf16 v[126:129], v[138:141], v[178:181], v[126:129]
	v_mfma_f32_16x16x32_bf16 v[94:97], v[146:149], v[178:181], v[94:97]
	v_mfma_f32_16x16x32_bf16 v[122:125], v[138:141], v[186:189], v[122:125]
	v_mfma_f32_16x16x32_bf16 v[90:93], v[146:149], v[186:189], v[90:93]
	v_mfma_f32_16x16x32_bf16 v[118:121], v[138:141], v[194:197], v[118:121]
	v_mfma_f32_16x16x32_bf16 v[86:89], v[146:149], v[194:197], v[86:89]
	s_waitcnt vmcnt(0)
	s_barrier
	s_setprio 0
	s_mov_b64 s[0:1], -1
	s_branch .LBB0_122
.Lhu_y:
	s_add_u32 s88, s2, 0x40000
	s_addc_u32 s89, s3, 0
	s_add_i32 m0, s61, 0xc000
	s_nop 0
	global_load_lds_dwordx4 v208, s[2:3]
	s_add_i32 m0, s61, 0xe000
	s_nop 0
	global_load_lds_dwordx4 v212, s[2:3]
	s_add_i32 m0, s61, 0x20000
	s_nop 0
	global_load_lds_dwordx4 v208, s[88:89]
	s_add_i32 m0, s61, 0x22000
	s_nop 0
	global_load_lds_dwordx4 v212, s[88:89]
	s_mov_b32 m0, s95
	s_nop 0
	global_load_lds_dwordx4 v206, s[84:85]
	s_mov_b32 m0, s96
	s_nop 0
	global_load_lds_dwordx4 v210, s[84:85]
	s_add_u32 s2, s2, 0x80
	s_addc_u32 s3, s3, 0
	s_add_u32 s84, s84, 0x80
	s_addc_u32 s85, s85, 0
.Lhu_yl:
	ds_read_b128 v[150:153], v248
	ds_read_b128 v[154:157], v248 offset:1024
	ds_read_b128 v[158:161], v248 offset:2048
	ds_read_b128 v[162:165], v248 offset:3072
	ds_read_b128 v[134:137], v249
	ds_read_b128 v[138:141], v249 offset:1024
	ds_read_b128 v[142:145], v249 offset:2048
	ds_read_b128 v[146:149], v249 offset:3072
	ds_read_b128 v[166:169], v250
	ds_read_b128 v[170:173], v250 offset:1024
	ds_read_b128 v[174:177], v250 offset:2048
	ds_read_b128 v[178:181], v250 offset:3072
	ds_read_b128 v[182:185], v250 offset:4096
	ds_read_b128 v[186:189], v250 offset:5120
	ds_read_b128 v[190:193], v250 offset:6144
	ds_read_b128 v[194:197], v250 offset:7168
	s_setprio 1
	s_waitcnt vmcnt(6) lgkmcnt(0)
	s_barrier
	s_add_u32 s88, s2, 0x40000
	s_addc_u32 s89, s3, 0
	s_mov_b32 m0, s73
	s_nop 0
	global_load_lds_dwordx4 v208, s[2:3]
	s_mov_b32 m0, s75
	s_nop 0
	global_load_lds_dwordx4 v212, s[2:3]
	s_mov_b32 m0, s92
	s_nop 0
	global_load_lds_dwordx4 v208, s[88:89]
	s_mov_b32 m0, s93
	s_nop 0
	global_load_lds_dwordx4 v212, s[88:89]
	s_mov_b32 m0, s61
	s_nop 0
	global_load_lds_dwordx4 v206, s[84:85]
	s_mov_b32 m0, s94
	s_nop 0
	global_load_lds_dwordx4 v210, s[84:85]
	s_add_u32 s2, s2, 0x80
	s_addc_u32 s3, s3, 0
	s_add_u32 s84, s84, 0x80
	s_addc_u32 s85, s85, 0
	v_mfma_f32_16x16x32_bf16 v[102:105], v[150:153], v[166:169], v[102:105]
	v_mfma_f32_16x16x32_bf16 v[70:73], v[158:161], v[166:169], v[70:73]
	v_mfma_f32_16x16x32_bf16 v[114:117], v[150:153], v[174:177], v[114:117]
	v_mfma_f32_16x16x32_bf16 v[82:85], v[158:161], v[174:177], v[82:85]
	v_mfma_f32_16x16x32_bf16 v[110:113], v[150:153], v[182:185], v[110:113]
	v_mfma_f32_16x16x32_bf16 v[78:81], v[158:161], v[182:185], v[78:81]
	v_mfma_f32_16x16x32_bf16 v[106:109], v[150:153], v[190:193], v[106:109]
	v_mfma_f32_16x16x32_bf16 v[74:77], v[158:161], v[190:193], v[74:77]
	v_mfma_f32_16x16x32_bf16 v[102:105], v[154:157], v[170:173], v[102:105]
	v_mfma_f32_16x16x32_bf16 v[70:73], v[162:165], v[170:173], v[70:73]
	v_mfma_f32_16x16x32_bf16 v[114:117], v[154:157], v[178:181], v[114:117]
	v_mfma_f32_16x16x32_bf16 v[82:85], v[162:165], v[178:181], v[82:85]
	v_mfma_f32_16x16x32_bf16 v[110:113], v[154:157], v[186:189], v[110:113]
	v_mfma_f32_16x16x32_bf16 v[78:81], v[162:165], v[186:189], v[78:81]
	v_mfma_f32_16x16x32_bf16 v[106:109], v[154:157], v[194:197], v[106:109]
	v_mfma_f32_16x16x32_bf16 v[74:77], v[162:165], v[194:197], v[74:77]
	v_mfma_f32_16x16x32_bf16 v[130:133], v[134:137], v[166:169], v[130:133]
	v_mfma_f32_16x16x32_bf16 v[98:101], v[142:145], v[166:169], v[98:101]
	v_mfma_f32_16x16x32_bf16 v[126:129], v[134:137], v[174:177], v[126:129]
	v_mfma_f32_16x16x32_bf16 v[94:97], v[142:145], v[174:177], v[94:97]
	v_mfma_f32_16x16x32_bf16 v[122:125], v[134:137], v[182:185], v[122:125]
	v_mfma_f32_16x16x32_bf16 v[90:93], v[142:145], v[182:185], v[90:93]
	v_mfma_f32_16x16x32_bf16 v[118:121], v[134:137], v[190:193], v[118:121]
	v_mfma_f32_16x16x32_bf16 v[86:89], v[142:145], v[190:193], v[86:89]
	v_mfma_f32_16x16x32_bf16 v[130:133], v[138:141], v[170:173], v[130:133]
	v_mfma_f32_16x16x32_bf16 v[98:101], v[146:149], v[170:173], v[98:101]
	v_mfma_f32_16x16x32_bf16 v[126:129], v[138:141], v[178:181], v[126:129]
	v_mfma_f32_16x16x32_bf16 v[94:97], v[146:149], v[178:181], v[94:97]
	v_mfma_f32_16x16x32_bf16 v[122:125], v[138:141], v[186:189], v[122:125]
	v_mfma_f32_16x16x32_bf16 v[90:93], v[146:149], v[186:189], v[90:93]
	v_mfma_f32_16x16x32_bf16 v[118:121], v[138:141], v[194:197], v[118:121]
	v_mfma_f32_16x16x32_bf16 v[86:89], v[146:149], v[194:197], v[86:89]
	s_barrier
	s_setprio 0
	ds_read_b128 v[150:153], v220
	ds_read_b128 v[154:157], v220 offset:1024
	ds_read_b128 v[158:161], v220 offset:2048
	ds_read_b128 v[162:165], v220 offset:3072
	ds_read_b128 v[134:137], v221
	ds_read_b128 v[138:141], v221 offset:1024
	ds_read_b128 v[142:145], v221 offset:2048
	ds_read_b128 v[146:149], v221 offset:3072
	ds_read_b128 v[166:169], v250 offset:32768
	ds_read_b128 v[170:173], v250 offset:33792
	ds_read_b128 v[174:177], v250 offset:34816
	ds_read_b128 v[178:181], v250 offset:35840
	ds_read_b128 v[182:185], v250 offset:36864
	ds_read_b128 v[186:189], v250 offset:37888
	ds_read_b128 v[190:193], v250 offset:38912
	ds_read_b128 v[194:197], v250 offset:39936
	s_setprio 1
	s_waitcnt vmcnt(6) lgkmcnt(0)
	s_barrier
	s_add_u32 s88, s2, 0x40000
	s_addc_u32 s89, s3, 0
	s_mov_b32 m0, s54
	s_nop 0
	global_load_lds_dwordx4 v208, s[2:3]
	s_mov_b32 m0, s55
	s_nop 0
	global_load_lds_dwordx4 v212, s[2:3]
	s_mov_b32 m0, s59
	s_nop 0
	global_load_lds_dwordx4 v208, s[88:89]
	s_mov_b32 m0, s24
	s_nop 0
	global_load_lds_dwordx4 v212, s[88:89]
	s_mov_b32 m0, s57
	s_nop 0
	global_load_lds_dwordx4 v206, s[84:85]
	s_mov_b32 m0, s58
	s_nop 0
	global_load_lds_dwordx4 v210, s[84:85]
	s_add_u32 s2, s2, 0x80
	s_addc_u32 s3, s3, 0
	s_add_u32 s84, s84, 0x80
	s_addc_u32 s85, s85, 0
	v_mfma_f32_16x16x32_bf16 v[102:105], v[150:153], v[166:169], v[102:105]
	v_mfma_f32_16x16x32_bf16 v[70:73], v[158:161], v[166:169], v[70:73]
	v_mfma_f32_16x16x32_bf16 v[114:117], v[150:153], v[174:177], v[114:117]
	v_mfma_f32_16x16x32_bf16 v[82:85], v[158:161], v[174:177], v[82:85]
	v_mfma_f32_16x16x32_bf16 v[110:113], v[150:153], v[182:185], v[110:113]
	v_mfma_f32_16x16x32_bf16 v[78:81], v[158:161], v[182:185], v[78:81]
	v_mfma_f32_16x16x32_bf16 v[106:109], v[150:153], v[190:193], v[106:109]
	v_mfma_f32_16x16x32_bf16 v[74:77], v[158:161], v[190:193], v[74:77]
	v_mfma_f32_16x16x32_bf16 v[102:105], v[154:157], v[170:173], v[102:105]
	v_mfma_f32_16x16x32_bf16 v[70:73], v[162:165], v[170:173], v[70:73]
	v_mfma_f32_16x16x32_bf16 v[114:117], v[154:157], v[178:181], v[114:117]
	v_mfma_f32_16x16x32_bf16 v[82:85], v[162:165], v[178:181], v[82:85]
	v_mfma_f32_16x16x32_bf16 v[110:113], v[154:157], v[186:189], v[110:113]
	v_mfma_f32_16x16x32_bf16 v[78:81], v[162:165], v[186:189], v[78:81]
	v_mfma_f32_16x16x32_bf16 v[106:109], v[154:157], v[194:197], v[106:109]
	v_mfma_f32_16x16x32_bf16 v[74:77], v[162:165], v[194:197], v[74:77]
	v_mfma_f32_16x16x32_bf16 v[130:133], v[134:137], v[166:169], v[130:133]
	v_mfma_f32_16x16x32_bf16 v[98:101], v[142:145], v[166:169], v[98:101]
	v_mfma_f32_16x16x32_bf16 v[126:129], v[134:137], v[174:177], v[126:129]
	v_mfma_f32_16x16x32_bf16 v[94:97], v[142:145], v[174:177], v[94:97]
	v_mfma_f32_16x16x32_bf16 v[122:125], v[134:137], v[182:185], v[122:125]
	v_mfma_f32_16x16x32_bf16 v[90:93], v[142:145], v[182:185], v[90:93]
	v_mfma_f32_16x16x32_bf16 v[118:121], v[134:137], v[190:193], v[118:121]
	v_mfma_f32_16x16x32_bf16 v[86:89], v[142:145], v[190:193], v[86:89]
	v_mfma_f32_16x16x32_bf16 v[130:133], v[138:141], v[170:173], v[130:133]
	v_mfma_f32_16x16x32_bf16 v[98:101], v[146:149], v[170:173], v[98:101]
	v_mfma_f32_16x16x32_bf16 v[126:129], v[138:141], v[178:181], v[126:129]
	v_mfma_f32_16x16x32_bf16 v[94:97], v[146:149], v[178:181], v[94:97]
	v_mfma_f32_16x16x32_bf16 v[122:125], v[138:141], v[186:189], v[122:125]
	v_mfma_f32_16x16x32_bf16 v[90:93], v[146:149], v[186:189], v[90:93]
	v_mfma_f32_16x16x32_bf16 v[118:121], v[138:141], v[194:197], v[118:121]
	v_mfma_f32_16x16x32_bf16 v[86:89], v[146:149], v[194:197], v[86:89]
	s_barrier
	s_setprio 0
	ds_read_b128 v[150:153], v222
	ds_read_b128 v[154:157], v222 offset:1024
	ds_read_b128 v[158:161], v222 offset:2048
	ds_read_b128 v[162:165], v222 offset:3072
	ds_read_b128 v[134:137], v223
	ds_read_b128 v[138:141], v223 offset:1024
	ds_read_b128 v[142:145], v223 offset:2048
	ds_read_b128 v[146:149], v223 offset:3072
	ds_read_b128 v[166:169], v250 offset:16384
	ds_read_b128 v[170:173], v250 offset:17408
	ds_read_b128 v[174:177], v250 offset:18432
	ds_read_b128 v[178:181], v250 offset:19456
	ds_read_b128 v[182:185], v250 offset:20480
	ds_read_b128 v[186:189], v250 offset:21504
	ds_read_b128 v[190:193], v250 offset:22528
	ds_read_b128 v[194:197], v250 offset:23552
	s_setprio 1
	s_waitcnt vmcnt(6) lgkmcnt(0)
	s_barrier
	s_add_u32 s88, s2, 0x40000
	s_addc_u32 s89, s3, 0
	s_add_i32 m0, s61, 0xc000
	s_nop 0
	global_load_lds_dwordx4 v208, s[2:3]
	s_add_i32 m0, s61, 0xe000
	s_nop 0
	global_load_lds_dwordx4 v212, s[2:3]
	s_add_i32 m0, s61, 0x20000
	s_nop 0
	global_load_lds_dwordx4 v208, s[88:89]
	s_add_i32 m0, s61, 0x22000
	s_nop 0
	global_load_lds_dwordx4 v212, s[88:89]
	s_mov_b32 m0, s95
	s_nop 0
	global_load_lds_dwordx4 v206, s[84:85]
	s_mov_b32 m0, s96
	s_nop 0
	global_load_lds_dwordx4 v210, s[84:85]
	s_add_u32 s2, s2, 0x80
	s_addc_u32 s3, s3, 0
	s_add_u32 s84, s84, 0x80
	s_addc_u32 s85, s85, 0
	v_mfma_f32_16x16x32_bf16 v[102:105], v[150:153], v[166:169], v[102:105]
	v_mfma_f32_16x16x32_bf16 v[70:73], v[158:161], v[166:169], v[70:73]
	v_mfma_f32_16x16x32_bf16 v[114:117], v[150:153], v[174:177], v[114:117]
	v_mfma_f32_16x16x32_bf16 v[82:85], v[158:161], v[174:177], v[82:85]
	v_mfma_f32_16x16x32_bf16 v[110:113], v[150:153], v[182:185], v[110:113]
	v_mfma_f32_16x16x32_bf16 v[78:81], v[158:161], v[182:185], v[78:81]
	v_mfma_f32_16x16x32_bf16 v[106:109], v[150:153], v[190:193], v[106:109]
	v_mfma_f32_16x16x32_bf16 v[74:77], v[158:161], v[190:193], v[74:77]
	v_mfma_f32_16x16x32_bf16 v[102:105], v[154:157], v[170:173], v[102:105]
	v_mfma_f32_16x16x32_bf16 v[70:73], v[162:165], v[170:173], v[70:73]
	v_mfma_f32_16x16x32_bf16 v[114:117], v[154:157], v[178:181], v[114:117]
	v_mfma_f32_16x16x32_bf16 v[82:85], v[162:165], v[178:181], v[82:85]
	v_mfma_f32_16x16x32_bf16 v[110:113], v[154:157], v[186:189], v[110:113]
	v_mfma_f32_16x16x32_bf16 v[78:81], v[162:165], v[186:189], v[78:81]
	v_mfma_f32_16x16x32_bf16 v[106:109], v[154:157], v[194:197], v[106:109]
	v_mfma_f32_16x16x32_bf16 v[74:77], v[162:165], v[194:197], v[74:77]
	v_mfma_f32_16x16x32_bf16 v[130:133], v[134:137], v[166:169], v[130:133]
	v_mfma_f32_16x16x32_bf16 v[98:101], v[142:145], v[166:169], v[98:101]
	v_mfma_f32_16x16x32_bf16 v[126:129], v[134:137], v[174:177], v[126:129]
	v_mfma_f32_16x16x32_bf16 v[94:97], v[142:145], v[174:177], v[94:97]
	v_mfma_f32_16x16x32_bf16 v[122:125], v[134:137], v[182:185], v[122:125]
	v_mfma_f32_16x16x32_bf16 v[90:93], v[142:145], v[182:185], v[90:93]
	v_mfma_f32_16x16x32_bf16 v[118:121], v[134:137], v[190:193], v[118:121]
	v_mfma_f32_16x16x32_bf16 v[86:89], v[142:145], v[190:193], v[86:89]
	v_mfma_f32_16x16x32_bf16 v[130:133], v[138:141], v[170:173], v[130:133]
	v_mfma_f32_16x16x32_bf16 v[98:101], v[146:149], v[170:173], v[98:101]
	v_mfma_f32_16x16x32_bf16 v[126:129], v[138:141], v[178:181], v[126:129]
	v_mfma_f32_16x16x32_bf16 v[94:97], v[146:149], v[178:181], v[94:97]
	v_mfma_f32_16x16x32_bf16 v[122:125], v[138:141], v[186:189], v[122:125]
	v_mfma_f32_16x16x32_bf16 v[90:93], v[146:149], v[186:189], v[90:93]
	v_mfma_f32_16x16x32_bf16 v[118:121], v[138:141], v[194:197], v[118:121]
	v_mfma_f32_16x16x32_bf16 v[86:89], v[146:149], v[194:197], v[86:89]
	s_barrier
	s_setprio 0
	s_add_i32 s45, s45, 1
	s_cmp_lt_u32 s45, 4
	s_cbranch_scc1 .Lhu_yl
	ds_read_b128 v[150:153], v248
	ds_read_b128 v[154:157], v248 offset:1024
	ds_read_b128 v[158:161], v248 offset:2048
	ds_read_b128 v[162:165], v248 offset:3072
	ds_read_b128 v[134:137], v249
	ds_read_b128 v[138:141], v249 offset:1024
	ds_read_b128 v[142:145], v249 offset:2048
	ds_read_b128 v[146:149], v249 offset:3072
	ds_read_b128 v[166:169], v250
	ds_read_b128 v[170:173], v250 offset:1024
	ds_read_b128 v[174:177], v250 offset:2048
	ds_read_b128 v[178:181], v250 offset:3072
	ds_read_b128 v[182:185], v250 offset:4096
	ds_read_b128 v[186:189], v250 offset:5120
	ds_read_b128 v[190:193], v250 offset:6144
	ds_read_b128 v[194:197], v250 offset:7168
	s_setprio 1
	s_waitcnt vmcnt(6) lgkmcnt(0)
	s_barrier
	s_add_u32 s88, s2, 0x40000
	s_addc_u32 s89, s3, 0
	s_mov_b32 m0, s73
	s_nop 0
	global_load_lds_dwordx4 v208, s[2:3]
	s_mov_b32 m0, s75
	s_nop 0
	global_load_lds_dwordx4 v212, s[2:3]
	s_mov_b32 m0, s92
	s_nop 0
	global_load_lds_dwordx4 v208, s[88:89]
	s_mov_b32 m0, s93
	s_nop 0
	global_load_lds_dwordx4 v212, s[88:89]
	s_mov_b32 m0, s61
	s_nop 0
	global_load_lds_dwordx4 v206, s[84:85]
	s_mov_b32 m0, s94
	s_nop 0
	global_load_lds_dwordx4 v210, s[84:85]
	s_add_u32 s2, s2, 0x80
	s_addc_u32 s3, s3, 0
	s_add_u32 s84, s84, 0x80
	s_addc_u32 s85, s85, 0
	v_mfma_f32_16x16x32_bf16 v[102:105], v[150:153], v[166:169], v[102:105]
	v_mfma_f32_16x16x32_bf16 v[70:73], v[158:161], v[166:169], v[70:73]
	v_mfma_f32_16x16x32_bf16 v[114:117], v[150:153], v[174:177], v[114:117]
	v_mfma_f32_16x16x32_bf16 v[82:85], v[158:161], v[174:177], v[82:85]
	v_mfma_f32_16x16x32_bf16 v[110:113], v[150:153], v[182:185], v[110:113]
	v_mfma_f32_16x16x32_bf16 v[78:81], v[158:161], v[182:185], v[78:81]
	v_mfma_f32_16x16x32_bf16 v[106:109], v[150:153], v[190:193], v[106:109]
	v_mfma_f32_16x16x32_bf16 v[74:77], v[158:161], v[190:193], v[74:77]
	v_mfma_f32_16x16x32_bf16 v[102:105], v[154:157], v[170:173], v[102:105]
	v_mfma_f32_16x16x32_bf16 v[70:73], v[162:165], v[170:173], v[70:73]
	v_mfma_f32_16x16x32_bf16 v[114:117], v[154:157], v[178:181], v[114:117]
	v_mfma_f32_16x16x32_bf16 v[82:85], v[162:165], v[178:181], v[82:85]
	v_mfma_f32_16x16x32_bf16 v[110:113], v[154:157], v[186:189], v[110:113]
	v_mfma_f32_16x16x32_bf16 v[78:81], v[162:165], v[186:189], v[78:81]
	v_mfma_f32_16x16x32_bf16 v[106:109], v[154:157], v[194:197], v[106:109]
	v_mfma_f32_16x16x32_bf16 v[74:77], v[162:165], v[194:197], v[74:77]
	v_mfma_f32_16x16x32_bf16 v[130:133], v[134:137], v[166:169], v[130:133]
	v_mfma_f32_16x16x32_bf16 v[98:101], v[142:145], v[166:169], v[98:101]
	v_mfma_f32_16x16x32_bf16 v[126:129], v[134:137], v[174:177], v[126:129]
	v_mfma_f32_16x16x32_bf16 v[94:97], v[142:145], v[174:177], v[94:97]
	v_mfma_f32_16x16x32_bf16 v[122:125], v[134:137], v[182:185], v[122:125]
	v_mfma_f32_16x16x32_bf16 v[90:93], v[142:145], v[182:185], v[90:93]
	v_mfma_f32_16x16x32_bf16 v[118:121], v[134:137], v[190:193], v[118:121]
	v_mfma_f32_16x16x32_bf16 v[86:89], v[142:145], v[190:193], v[86:89]
	v_mfma_f32_16x16x32_bf16 v[130:133], v[138:141], v[170:173], v[130:133]
	v_mfma_f32_16x16x32_bf16 v[98:101], v[146:149], v[170:173], v[98:101]
	v_mfma_f32_16x16x32_bf16 v[126:129], v[138:141], v[178:181], v[126:129]
	v_mfma_f32_16x16x32_bf16 v[94:97], v[146:149], v[178:181], v[94:97]
	v_mfma_f32_16x16x32_bf16 v[122:125], v[138:141], v[186:189], v[122:125]
	v_mfma_f32_16x16x32_bf16 v[90:93], v[146:149], v[186:189], v[90:93]
	v_mfma_f32_16x16x32_bf16 v[118:121], v[138:141], v[194:197], v[118:121]
	v_mfma_f32_16x16x32_bf16 v[86:89], v[146:149], v[194:197], v[86:89]
	s_barrier
	s_setprio 0
	ds_read_b128 v[150:153], v220
	ds_read_b128 v[154:157], v220 offset:1024
	ds_read_b128 v[158:161], v220 offset:2048
	ds_read_b128 v[162:165], v220 offset:3072
	ds_read_b128 v[134:137], v221
	ds_read_b128 v[138:141], v221 offset:1024
	ds_read_b128 v[142:145], v221 offset:2048
	ds_read_b128 v[146:149], v221 offset:3072
	ds_read_b128 v[166:169], v250 offset:32768
	ds_read_b128 v[170:173], v250 offset:33792
	ds_read_b128 v[174:177], v250 offset:34816
	ds_read_b128 v[178:181], v250 offset:35840
	ds_read_b128 v[182:185], v250 offset:36864
	ds_read_b128 v[186:189], v250 offset:37888
	ds_read_b128 v[190:193], v250 offset:38912
	ds_read_b128 v[194:197], v250 offset:39936
	s_setprio 1
	s_waitcnt vmcnt(6) lgkmcnt(0)
	s_barrier
	v_mfma_f32_16x16x32_bf16 v[102:105], v[150:153], v[166:169], v[102:105]
	v_mfma_f32_16x16x32_bf16 v[70:73], v[158:161], v[166:169], v[70:73]
	v_mfma_f32_16x16x32_bf16 v[114:117], v[150:153], v[174:177], v[114:117]
	v_mfma_f32_16x16x32_bf16 v[82:85], v[158:161], v[174:177], v[82:85]
	v_mfma_f32_16x16x32_bf16 v[110:113], v[150:153], v[182:185], v[110:113]
	v_mfma_f32_16x16x32_bf16 v[78:81], v[158:161], v[182:185], v[78:81]
	v_mfma_f32_16x16x32_bf16 v[106:109], v[150:153], v[190:193], v[106:109]
	v_mfma_f32_16x16x32_bf16 v[74:77], v[158:161], v[190:193], v[74:77]
	v_mfma_f32_16x16x32_bf16 v[102:105], v[154:157], v[170:173], v[102:105]
	v_mfma_f32_16x16x32_bf16 v[70:73], v[162:165], v[170:173], v[70:73]
	v_mfma_f32_16x16x32_bf16 v[114:117], v[154:157], v[178:181], v[114:117]
	v_mfma_f32_16x16x32_bf16 v[82:85], v[162:165], v[178:181], v[82:85]
	v_mfma_f32_16x16x32_bf16 v[110:113], v[154:157], v[186:189], v[110:113]
	v_mfma_f32_16x16x32_bf16 v[78:81], v[162:165], v[186:189], v[78:81]
	v_mfma_f32_16x16x32_bf16 v[106:109], v[154:157], v[194:197], v[106:109]
	v_mfma_f32_16x16x32_bf16 v[74:77], v[162:165], v[194:197], v[74:77]
	v_mfma_f32_16x16x32_bf16 v[130:133], v[134:137], v[166:169], v[130:133]
	v_mfma_f32_16x16x32_bf16 v[98:101], v[142:145], v[166:169], v[98:101]
	v_mfma_f32_16x16x32_bf16 v[126:129], v[134:137], v[174:177], v[126:129]
	v_mfma_f32_16x16x32_bf16 v[94:97], v[142:145], v[174:177], v[94:97]
	v_mfma_f32_16x16x32_bf16 v[122:125], v[134:137], v[182:185], v[122:125]
	v_mfma_f32_16x16x32_bf16 v[90:93], v[142:145], v[182:185], v[90:93]
	v_mfma_f32_16x16x32_bf16 v[118:121], v[134:137], v[190:193], v[118:121]
	v_mfma_f32_16x16x32_bf16 v[86:89], v[142:145], v[190:193], v[86:89]
	v_mfma_f32_16x16x32_bf16 v[130:133], v[138:141], v[170:173], v[130:133]
	v_mfma_f32_16x16x32_bf16 v[98:101], v[146:149], v[170:173], v[98:101]
	v_mfma_f32_16x16x32_bf16 v[126:129], v[138:141], v[178:181], v[126:129]
	v_mfma_f32_16x16x32_bf16 v[94:97], v[146:149], v[178:181], v[94:97]
	v_mfma_f32_16x16x32_bf16 v[122:125], v[138:141], v[186:189], v[122:125]
	v_mfma_f32_16x16x32_bf16 v[90:93], v[146:149], v[186:189], v[90:93]
	v_mfma_f32_16x16x32_bf16 v[118:121], v[138:141], v[194:197], v[118:121]
	v_mfma_f32_16x16x32_bf16 v[86:89], v[146:149], v[194:197], v[86:89]
	s_barrier
	s_setprio 0
	ds_read_b128 v[150:153], v222
	ds_read_b128 v[154:157], v222 offset:1024
	ds_read_b128 v[158:161], v222 offset:2048
	ds_read_b128 v[162:165], v222 offset:3072
	ds_read_b128 v[134:137], v223
	ds_read_b128 v[138:141], v223 offset:1024
	ds_read_b128 v[142:145], v223 offset:2048
	ds_read_b128 v[146:149], v223 offset:3072
	ds_read_b128 v[166:169], v250 offset:16384
	ds_read_b128 v[170:173], v250 offset:17408
	ds_read_b128 v[174:177], v250 offset:18432
	ds_read_b128 v[178:181], v250 offset:19456
	ds_read_b128 v[182:185], v250 offset:20480
	ds_read_b128 v[186:189], v250 offset:21504
	ds_read_b128 v[190:193], v250 offset:22528
	ds_read_b128 v[194:197], v250 offset:23552
	s_setprio 1
	s_waitcnt vmcnt(0) lgkmcnt(0)
	s_barrier
	v_mfma_f32_16x16x32_bf16 v[102:105], v[150:153], v[166:169], v[102:105]
	v_mfma_f32_16x16x32_bf16 v[70:73], v[158:161], v[166:169], v[70:73]
	v_mfma_f32_16x16x32_bf16 v[114:117], v[150:153], v[174:177], v[114:117]
	v_mfma_f32_16x16x32_bf16 v[82:85], v[158:161], v[174:177], v[82:85]
	v_mfma_f32_16x16x32_bf16 v[110:113], v[150:153], v[182:185], v[110:113]
	v_mfma_f32_16x16x32_bf16 v[78:81], v[158:161], v[182:185], v[78:81]
	v_mfma_f32_16x16x32_bf16 v[106:109], v[150:153], v[190:193], v[106:109]
	v_mfma_f32_16x16x32_bf16 v[74:77], v[158:161], v[190:193], v[74:77]
	v_mfma_f32_16x16x32_bf16 v[102:105], v[154:157], v[170:173], v[102:105]
	v_mfma_f32_16x16x32_bf16 v[70:73], v[162:165], v[170:173], v[70:73]
	v_mfma_f32_16x16x32_bf16 v[114:117], v[154:157], v[178:181], v[114:117]
	v_mfma_f32_16x16x32_bf16 v[82:85], v[162:165], v[178:181], v[82:85]
	v_mfma_f32_16x16x32_bf16 v[110:113], v[154:157], v[186:189], v[110:113]
	v_mfma_f32_16x16x32_bf16 v[78:81], v[162:165], v[186:189], v[78:81]
	v_mfma_f32_16x16x32_bf16 v[106:109], v[154:157], v[194:197], v[106:109]
	v_mfma_f32_16x16x32_bf16 v[74:77], v[162:165], v[194:197], v[74:77]
	v_mfma_f32_16x16x32_bf16 v[130:133], v[134:137], v[166:169], v[130:133]
	v_mfma_f32_16x16x32_bf16 v[98:101], v[142:145], v[166:169], v[98:101]
	v_mfma_f32_16x16x32_bf16 v[126:129], v[134:137], v[174:177], v[126:129]
	v_mfma_f32_16x16x32_bf16 v[94:97], v[142:145], v[174:177], v[94:97]
	v_mfma_f32_16x16x32_bf16 v[122:125], v[134:137], v[182:185], v[122:125]
	v_mfma_f32_16x16x32_bf16 v[90:93], v[142:145], v[182:185], v[90:93]
	v_mfma_f32_16x16x32_bf16 v[118:121], v[134:137], v[190:193], v[118:121]
	v_mfma_f32_16x16x32_bf16 v[86:89], v[142:145], v[190:193], v[86:89]
	v_mfma_f32_16x16x32_bf16 v[130:133], v[138:141], v[170:173], v[130:133]
	v_mfma_f32_16x16x32_bf16 v[98:101], v[146:149], v[170:173], v[98:101]
	v_mfma_f32_16x16x32_bf16 v[126:129], v[138:141], v[178:181], v[126:129]
	v_mfma_f32_16x16x32_bf16 v[94:97], v[146:149], v[178:181], v[94:97]
	v_mfma_f32_16x16x32_bf16 v[122:125], v[138:141], v[186:189], v[122:125]
	v_mfma_f32_16x16x32_bf16 v[90:93], v[146:149], v[186:189], v[90:93]
	v_mfma_f32_16x16x32_bf16 v[118:121], v[138:141], v[194:197], v[118:121]
	v_mfma_f32_16x16x32_bf16 v[86:89], v[146:149], v[194:197], v[86:89]
	s_barrier
	s_setprio 0
	ds_read_b128 v[150:153], v248
	ds_read_b128 v[154:157], v248 offset:1024
	ds_read_b128 v[158:161], v248 offset:2048
	ds_read_b128 v[162:165], v248 offset:3072
	ds_read_b128 v[134:137], v249
	ds_read_b128 v[138:141], v249 offset:1024
	ds_read_b128 v[142:145], v249 offset:2048
	ds_read_b128 v[146:149], v249 offset:3072
	ds_read_b128 v[166:169], v250
	ds_read_b128 v[170:173], v250 offset:1024
	ds_read_b128 v[174:177], v250 offset:2048
	ds_read_b128 v[178:181], v250 offset:3072
	ds_read_b128 v[182:185], v250 offset:4096
	ds_read_b128 v[186:189], v250 offset:5120
	ds_read_b128 v[190:193], v250 offset:6144
	ds_read_b128 v[194:197], v250 offset:7168
	s_setprio 1
	s_waitcnt vmcnt(0) lgkmcnt(0)
	s_barrier
	v_mfma_f32_16x16x32_bf16 v[102:105], v[150:153], v[166:169], v[102:105]
	v_mfma_f32_16x16x32_bf16 v[70:73], v[158:161], v[166:169], v[70:73]
	v_mfma_f32_16x16x32_bf16 v[114:117], v[150:153], v[174:177], v[114:117]
	v_mfma_f32_16x16x32_bf16 v[82:85], v[158:161], v[174:177], v[82:85]
	v_mfma_f32_16x16x32_bf16 v[110:113], v[150:153], v[182:185], v[110:113]
	v_mfma_f32_16x16x32_bf16 v[78:81], v[158:161], v[182:185], v[78:81]
	v_mfma_f32_16x16x32_bf16 v[106:109], v[150:153], v[190:193], v[106:109]
	v_mfma_f32_16x16x32_bf16 v[74:77], v[158:161], v[190:193], v[74:77]
	v_mfma_f32_16x16x32_bf16 v[102:105], v[154:157], v[170:173], v[102:105]
	v_mfma_f32_16x16x32_bf16 v[70:73], v[162:165], v[170:173], v[70:73]
	v_mfma_f32_16x16x32_bf16 v[114:117], v[154:157], v[178:181], v[114:117]
	v_mfma_f32_16x16x32_bf16 v[82:85], v[162:165], v[178:181], v[82:85]
	v_mfma_f32_16x16x32_bf16 v[110:113], v[154:157], v[186:189], v[110:113]
	v_mfma_f32_16x16x32_bf16 v[78:81], v[162:165], v[186:189], v[78:81]
	v_mfma_f32_16x16x32_bf16 v[106:109], v[154:157], v[194:197], v[106:109]
	v_mfma_f32_16x16x32_bf16 v[74:77], v[162:165], v[194:197], v[74:77]
	v_mfma_f32_16x16x32_bf16 v[130:133], v[134:137], v[166:169], v[130:133]
	v_mfma_f32_16x16x32_bf16 v[98:101], v[142:145], v[166:169], v[98:101]
	v_mfma_f32_16x16x32_bf16 v[126:129], v[134:137], v[174:177], v[126:129]
	v_mfma_f32_16x16x32_bf16 v[94:97], v[142:145], v[174:177], v[94:97]
	v_mfma_f32_16x16x32_bf16 v[122:125], v[134:137], v[182:185], v[122:125]
	v_mfma_f32_16x16x32_bf16 v[90:93], v[142:145], v[182:185], v[90:93]
	v_mfma_f32_16x16x32_bf16 v[118:121], v[134:137], v[190:193], v[118:121]
	v_mfma_f32_16x16x32_bf16 v[86:89], v[142:145], v[190:193], v[86:89]
	v_mfma_f32_16x16x32_bf16 v[130:133], v[138:141], v[170:173], v[130:133]
	v_mfma_f32_16x16x32_bf16 v[98:101], v[146:149], v[170:173], v[98:101]
	v_mfma_f32_16x16x32_bf16 v[126:129], v[138:141], v[178:181], v[126:129]
	v_mfma_f32_16x16x32_bf16 v[94:97], v[146:149], v[178:181], v[94:97]
	v_mfma_f32_16x16x32_bf16 v[122:125], v[138:141], v[186:189], v[122:125]
	v_mfma_f32_16x16x32_bf16 v[90:93], v[146:149], v[186:189], v[90:93]
	v_mfma_f32_16x16x32_bf16 v[118:121], v[138:141], v[194:197], v[118:121]
	v_mfma_f32_16x16x32_bf16 v[86:89], v[146:149], v[194:197], v[86:89]
	s_barrier
	s_setprio 0
	s_mov_b64 s[0:1], -1
	s_branch .LBB0_122
